# software-pipelined tile loads in the two largest weight-conversion loops (next tile's loads issued after the current tile's LDS writes)
# baseline (speedup 1.0000x reference)
.LBB0_463:
	v_readlane_b32 s24, v254, 49
	v_readlane_b32 s26, v254, 51
	v_readlane_b32 s27, v254, 52
	v_readlane_b32 s25, v254, 50
	v_readlane_b32 s28, v254, 35
	v_readlane_b32 s26, v254, 37
	v_readlane_b32 s30, v254, 39
	s_cmp_lt_i32 s46, 0
	v_readlane_b32 s29, v254, 36
	v_readlane_b32 s27, v254, 38
	v_readlane_b32 s31, v254, 40
	s_cbranch_scc1 .LBB0_509
	v_readlane_b32 s4, v254, 41
	v_readlane_b32 s5, v254, 42
	s_load_dwordx2 s[4:5], s[4:5], 0x120
	s_sub_i32 s0, s54, s1
	s_cmp_ge_i32 s2, s1
	v_mov_b32_e32 v4, v197
	s_cselect_b64 s[10:11], -1, 0
	s_cmp_lt_i32 s2, s1
	s_mov_b32 s19, 0x8600
	s_cbranch_scc1 .LBB0_470
	s_sub_i32 s6, s2, s1
	s_cmpk_gt_i32 s6, 0x87f
	s_cbranch_scc1 .LBB0_470
	v_readlane_b32 s8, v254, 41
	v_readlane_b32 s9, v254, 42
	s_load_dwordx2 s[8:9], s[8:9], 0x40
	v_lshlrev_b32_e32 v5, 3, v4
	s_waitcnt vmcnt(0)
	v_and_b32_e32 v6, 56, v5
	v_lshlrev_b32_e32 v5, 2, v4
	v_ashrrev_i32_e32 v1, 4, v4
	v_and_b32_e32 v8, 60, v5
	s_movk_i32 s3, 0x110
	v_ashrrev_i32_e32 v3, 3, v4
	v_lshlrev_b32_e32 v5, 2, v8
	v_mul_lo_u32 v7, v1, s3
	s_mul_i32 s12, s46, 0x2180000
	v_add3_u32 v16, 0, v5, v7
	v_add3_u32 v17, 0, v7, v5
	v_lshlrev_b32_e32 v5, 2, v3
	s_mul_hi_u32 s7, s46, 0x2180000
	s_waitcnt lgkmcnt(0)
	s_add_u32 s8, s8, s12
	v_and_b32_e32 v5, 0x8c, v5
	s_addc_u32 s9, s9, s7
	v_add_u32_e32 v5, 0, v5
	v_and_b32_e32 v7, 16, v3
	v_and_b32_e32 v4, 0x60, v4
	s_add_u32 s12, s4, 0x1198100
	v_add3_u32 v4, v5, v7, v4
	v_mul_u32_u24_e32 v5, 0x110, v6
	s_addc_u32 s13, s5, 0
	s_lshl_b32 s7, s6, 6
	s_lshl_b32 s16, s0, 6
	v_lshlrev_b32_e32 v12, 2, v8
	v_add_u32_e32 v18, v4, v5
	v_lshlrev_b32_e32 v14, 1, v6
	s_branch .LBB0_468
.LBB0_468:
	s_ashr_i32 s14, s6, 31
	s_lshr_b32 s14, s14, 28
	s_add_i32 s14, s6, s14
	s_ashr_i32 s14, s14, 4
	s_lshl_b32 s15, s14, 10
	s_lshl_b32 s17, s14, 6
	s_sub_i32 s18, 0, s15
	s_add_i32 s14, s17, 0xffffff80
	s_cmpk_gt_i32 s6, 0x37f
	s_cselect_b32 s14, s14, 0x2180
	s_cmpk_lt_i32 s6, 0x360
	s_cselect_b32 s14, s17, s14
	v_mov_b32_e32 v4, 0
	s_cmpk_gt_i32 s14, 0x217f
	v_mov_b32_e32 v5, 0
	v_mov_b32_e32 v6, 0
	v_mov_b32_e32 v7, 0
	v_mov_b32_e32 v8, 0
	v_mov_b32_e32 v9, 0
	v_mov_b32_e32 v10, 0
	v_mov_b32_e32 v11, 0
	s_cbranch_scc1 .Lcvp1_ent
	s_add_i32 s15, s18, s7
	v_add_u32_e32 v8, s15, v1
	v_mov_b64_e32 v[4:5], s[8:9]
	v_mad_i64_i32 v[6:7], s[20:21], v8, s19, v[4:5]
	s_ashr_i32 s15, s14, 31
	v_add_u32_e32 v8, 32, v8
	s_lshl_b64 s[14:15], s[14:15], 2
	v_mad_i64_i32 v[4:5], s[20:21], v8, s19, v[4:5]
	v_lshl_add_u64 v[6:7], v[6:7], 0, s[14:15]
	v_mov_b32_e32 v13, v2
	v_lshl_add_u64 v[4:5], v[4:5], 0, s[14:15]
	v_lshl_add_u64 v[6:7], v[6:7], 0, v[12:13]
	v_lshl_add_u64 v[8:9], v[4:5], 0, v[12:13]
	global_load_dwordx4 v[4:7], v[6:7], off
	s_nop 0
	global_load_dwordx4 v[8:11], v[8:9], off
.Lcvp1_ent:
	s_waitcnt vmcnt(0)
.LBB0_467:
	s_barrier
	s_waitcnt vmcnt(2)
	ds_write_b128 v16, v[4:7]
	s_waitcnt vmcnt(1)
	ds_write_b128 v17, v[8:11] offset:8704
	s_add_i32 s14, s7, s18
	s_ashr_i32 s15, s14, 31
	v_add_u32_e32 v100, s17, v3
	v_ashrrev_i32_e32 v101, 31, v100
	v_lshlrev_b64 v[100:101], 11, v[100:101]
	v_lshl_add_u64 v[100:101], s[12:13], 0, v[100:101]
	v_lshl_add_u64 v[100:101], s[14:15], 1, v[100:101]
	v_mov_b32_e32 v15, v2
	v_lshl_add_u64 v[100:101], v[100:101], 0, v[14:15]
	s_add_i32 s6, s6, s0
	s_add_i32 s7, s7, s16
	s_cmpk_lt_i32 s6, 0x880
	s_cbranch_scc0 .Lcvp1_pfd
	s_ashr_i32 s14, s6, 31
	s_lshr_b32 s14, s14, 28
	s_add_i32 s14, s6, s14
	s_ashr_i32 s14, s14, 4
	s_lshl_b32 s15, s14, 10
	s_lshl_b32 s17, s14, 6
	s_sub_i32 s18, 0, s15
	s_add_i32 s14, s17, 0xffffff80
	s_cmpk_gt_i32 s6, 0x37f
	s_cselect_b32 s14, s14, 0x2180
	s_cmpk_lt_i32 s6, 0x360
	s_cselect_b32 s14, s17, s14
	v_mov_b32_e32 v4, 0
	s_cmpk_gt_i32 s14, 0x217f
	v_mov_b32_e32 v5, 0
	v_mov_b32_e32 v6, 0
	v_mov_b32_e32 v7, 0
	v_mov_b32_e32 v8, 0
	v_mov_b32_e32 v9, 0
	v_mov_b32_e32 v10, 0
	v_mov_b32_e32 v11, 0
	s_cbranch_scc1 .Lcvp1_pfd
	s_add_i32 s15, s18, s7
	v_add_u32_e32 v8, s15, v1
	v_mov_b64_e32 v[4:5], s[8:9]
	v_mad_i64_i32 v[6:7], s[20:21], v8, s19, v[4:5]
	s_ashr_i32 s15, s14, 31
	v_add_u32_e32 v8, 32, v8
	s_lshl_b64 s[14:15], s[14:15], 2
	v_mad_i64_i32 v[4:5], s[20:21], v8, s19, v[4:5]
	v_lshl_add_u64 v[6:7], v[6:7], 0, s[14:15]
	v_mov_b32_e32 v13, v2
	v_lshl_add_u64 v[4:5], v[4:5], 0, s[14:15]
	v_lshl_add_u64 v[6:7], v[6:7], 0, v[12:13]
	v_lshl_add_u64 v[8:9], v[4:5], 0, v[12:13]
	global_load_dwordx4 v[4:7], v[6:7], off
	s_nop 0
	global_load_dwordx4 v[8:11], v[8:9], off
.Lcvp1_pfd:
	v_add_u32_e32 v102, 0x400, v18
	s_waitcnt lgkmcnt(0)
	s_barrier
	ds_read2_b32 v[88:89], v102 offset0:152 offset1:220
	ds_read2_b32 v[90:91], v102 offset0:16 offset1:84
	ds_read2_b32 v[92:93], v18 offset0:136 offset1:204
	ds_read2_b32 v[94:95], v18 offset1:68
	s_waitcnt lgkmcnt(2)
	v_cvt_pk_f16_f32 v98, v90, v91
	v_cvt_pk_f16_f32 v99, v88, v89
	s_waitcnt lgkmcnt(1)
	v_cvt_pk_f16_f32 v97, v92, v93
	s_waitcnt lgkmcnt(0)
	v_cvt_pk_f16_f32 v96, v94, v95
	global_store_dwordx4 v[100:101], v[96:99], off
	s_cmpk_lt_i32 s6, 0x880
	s_cbranch_scc1 .LBB0_467
.LBB0_470:
	v_cndmask_b32_e64 v1, 0, 1, s[10:11]
	v_mov_b32_e32 v4, v197
	v_cmp_ne_u32_e64 s[8:9], 1, v1
	s_andn2_b64 vcc, exec, s[10:11]
	s_cbranch_vccnz .LBB0_476
	s_sub_i32 s6, s2, s1
	s_cmpk_gt_i32 s6, 0x57f
	s_cbranch_scc1 .LBB0_476
	v_readlane_b32 s10, v254, 41
	v_readlane_b32 s11, v254, 42
	s_load_dwordx2 s[10:11], s[10:11], 0x100
	v_lshlrev_b32_e32 v5, 3, v4
	s_waitcnt vmcnt(0)
	v_and_b32_e32 v6, 56, v5
	v_lshlrev_b32_e32 v5, 2, v4
	v_ashrrev_i32_e32 v1, 4, v4
	v_and_b32_e32 v8, 60, v5
	s_movk_i32 s3, 0x110
	v_ashrrev_i32_e32 v3, 3, v4
	v_lshlrev_b32_e32 v5, 2, v8
	v_mul_lo_u32 v7, v1, s3
	s_mul_i32 s12, s46, 0x1600000
	v_add3_u32 v16, 0, v5, v7
	v_add3_u32 v17, 0, v7, v5
	v_lshlrev_b32_e32 v5, 2, v3
	s_mul_hi_u32 s7, s46, 0x1600000
	s_waitcnt lgkmcnt(0)
	s_add_u32 s10, s10, s12
	v_and_b32_e32 v5, 0x8c, v5
	s_addc_u32 s11, s11, s7
	v_add_u32_e32 v5, 0, v5
	v_and_b32_e32 v7, 16, v3
	v_and_b32_e32 v4, 0x60, v4
	s_add_u32 s12, s4, 0x2298100
	v_add3_u32 v4, v5, v7, v4
	v_mul_u32_u24_e32 v5, 0x110, v6
	s_addc_u32 s13, s5, 0
	s_lshl_b32 s7, s6, 6
	s_lshl_b32 s16, s0, 6
	v_lshlrev_b32_e32 v12, 2, v8
	v_add_u32_e32 v18, v4, v5
	v_lshlrev_b32_e32 v14, 1, v6
	s_movk_i32 s3, 0x5800
	s_branch .LBB0_474
.LBB0_474:
	s_ashr_i32 s14, s6, 31
	s_lshr_b32 s14, s14, 28
	s_add_i32 s14, s6, s14
	s_ashr_i32 s14, s14, 4
	s_lshl_b32 s15, s14, 10
	s_lshl_b32 s17, s14, 6
	s_lshl_b32 s14, s14, 5
	s_sub_i32 s18, 0, s15
	s_and_b32 s15, s17, 0xc0
	s_and_b32 s14, s14, 0xffffff80
	s_or_b32 s19, s14, s15
	s_add_i32 s14, s15, s14
	s_addk_i32 s14, 0xa80
	s_cmpk_lt_u32 s15, 0x80
	s_cselect_b32 s14, s19, s14
	v_mov_b32_e32 v4, 0
	s_cmpk_gt_i32 s14, 0x15ff
	v_mov_b32_e32 v5, 0
	v_mov_b32_e32 v6, 0
	v_mov_b32_e32 v7, 0
	v_mov_b32_e32 v8, 0
	v_mov_b32_e32 v9, 0
	v_mov_b32_e32 v10, 0
	v_mov_b32_e32 v11, 0
	s_cbranch_scc1 .Lcvp2_ent
	s_add_i32 s15, s18, s7
	v_add_u32_e32 v8, s15, v1
	v_mov_b64_e32 v[4:5], s[10:11]
	v_mad_i64_i32 v[6:7], s[20:21], v8, s3, v[4:5]
	s_ashr_i32 s15, s14, 31
	v_add_u32_e32 v8, 32, v8
	s_lshl_b64 s[14:15], s[14:15], 2
	v_mad_i64_i32 v[4:5], s[20:21], v8, s3, v[4:5]
	v_lshl_add_u64 v[6:7], v[6:7], 0, s[14:15]
	v_mov_b32_e32 v13, v2
	v_lshl_add_u64 v[4:5], v[4:5], 0, s[14:15]
	v_lshl_add_u64 v[6:7], v[6:7], 0, v[12:13]
	v_lshl_add_u64 v[8:9], v[4:5], 0, v[12:13]
	global_load_dwordx4 v[4:7], v[6:7], off
	s_nop 0
	global_load_dwordx4 v[8:11], v[8:9], off
.Lcvp2_ent:
	s_waitcnt vmcnt(0)
.LBB0_473:
	s_barrier
	s_waitcnt vmcnt(2)
	ds_write_b128 v16, v[4:7]
	s_waitcnt vmcnt(1)
	ds_write_b128 v17, v[8:11] offset:8704
	s_add_i32 s14, s7, s18
	s_ashr_i32 s15, s14, 31
	v_add_u32_e32 v100, s17, v3
	v_ashrrev_i32_e32 v101, 31, v100
	v_lshlrev_b64 v[100:101], 11, v[100:101]
	v_lshl_add_u64 v[100:101], s[12:13], 0, v[100:101]
	v_lshl_add_u64 v[100:101], s[14:15], 1, v[100:101]
	v_mov_b32_e32 v15, v2
	v_lshl_add_u64 v[100:101], v[100:101], 0, v[14:15]
	s_add_i32 s6, s6, s0
	s_add_i32 s7, s7, s16
	s_cmpk_lt_i32 s6, 0x580
	s_cbranch_scc0 .Lcvp2_pfd
	s_ashr_i32 s14, s6, 31
	s_lshr_b32 s14, s14, 28
	s_add_i32 s14, s6, s14
	s_ashr_i32 s14, s14, 4
	s_lshl_b32 s15, s14, 10
	s_lshl_b32 s17, s14, 6
	s_lshl_b32 s14, s14, 5
	s_sub_i32 s18, 0, s15
	s_and_b32 s15, s17, 0xc0
	s_and_b32 s14, s14, 0xffffff80
	s_or_b32 s19, s14, s15
	s_add_i32 s14, s15, s14
	s_addk_i32 s14, 0xa80
	s_cmpk_lt_u32 s15, 0x80
	s_cselect_b32 s14, s19, s14
	v_mov_b32_e32 v4, 0
	s_cmpk_gt_i32 s14, 0x15ff
	v_mov_b32_e32 v5, 0
	v_mov_b32_e32 v6, 0
	v_mov_b32_e32 v7, 0
	v_mov_b32_e32 v8, 0
	v_mov_b32_e32 v9, 0
	v_mov_b32_e32 v10, 0
	v_mov_b32_e32 v11, 0
	s_cbranch_scc1 .Lcvp2_pfd
	s_add_i32 s15, s18, s7
	v_add_u32_e32 v8, s15, v1
	v_mov_b64_e32 v[4:5], s[10:11]
	v_mad_i64_i32 v[6:7], s[20:21], v8, s3, v[4:5]
	s_ashr_i32 s15, s14, 31
	v_add_u32_e32 v8, 32, v8
	s_lshl_b64 s[14:15], s[14:15], 2
	v_mad_i64_i32 v[4:5], s[20:21], v8, s3, v[4:5]
	v_lshl_add_u64 v[6:7], v[6:7], 0, s[14:15]
	v_mov_b32_e32 v13, v2
	v_lshl_add_u64 v[4:5], v[4:5], 0, s[14:15]
	v_lshl_add_u64 v[6:7], v[6:7], 0, v[12:13]
	v_lshl_add_u64 v[8:9], v[4:5], 0, v[12:13]
	global_load_dwordx4 v[4:7], v[6:7], off
	s_nop 0
	global_load_dwordx4 v[8:11], v[8:9], off
.Lcvp2_pfd:
	v_add_u32_e32 v102, 0x400, v18
	s_waitcnt lgkmcnt(0)
	s_barrier
	ds_read2_b32 v[88:89], v102 offset0:152 offset1:220
	ds_read2_b32 v[90:91], v102 offset0:16 offset1:84
	ds_read2_b32 v[92:93], v18 offset0:136 offset1:204
	ds_read2_b32 v[94:95], v18 offset1:68
	s_waitcnt lgkmcnt(2)
	v_cvt_pk_f16_f32 v98, v90, v91
	v_cvt_pk_f16_f32 v99, v88, v89
	s_waitcnt lgkmcnt(1)
	v_cvt_pk_f16_f32 v97, v92, v93
	s_waitcnt lgkmcnt(0)
	v_cvt_pk_f16_f32 v96, v94, v95
	global_store_dwordx4 v[100:101], v[96:99], off
	s_cmpk_lt_i32 s6, 0x580
	s_cbranch_scc1 .LBB0_473
